# barrier set-up: 16 arrival-counter loads off one base behind one wait (on top of MIX conversion + readout epilogue changes)
# speedup vs baseline: 1.0026x; 1.0026x over previous
.LBB0_1081:
	global_load_dword v4, v1, s[48:49] sc1
	global_load_dword v0, v1, s[48:49] offset:256 sc1
	global_load_dword v2, v1, s[48:49] offset:512 sc1
	global_load_dword v3, v1, s[48:49] offset:768 sc1
	global_load_dword v5, v1, s[48:49] offset:1024 sc1
	global_load_dword v6, v1, s[48:49] offset:1280 sc1
	global_load_dword v7, v1, s[48:49] offset:1536 sc1
	global_load_dword v8, v1, s[48:49] offset:1792 sc1
	global_load_dword v9, v1, s[48:49] offset:2048 sc1
	global_load_dword v10, v1, s[48:49] offset:2304 sc1
	global_load_dword v11, v1, s[48:49] offset:2560 sc1
	global_load_dword v12, v1, s[48:49] offset:2816 sc1
	global_load_dword v13, v1, s[48:49] offset:3072 sc1
	global_load_dword v14, v1, s[48:49] offset:3328 sc1
	global_load_dword v15, v1, s[48:49] offset:3584 sc1
	global_load_dword v16, v1, s[48:49] offset:3840 sc1
	s_mov_b64 s[10:11], -1
	s_mov_b64 s[8:9], -1
	s_waitcnt vmcnt(0) lgkmcnt(0)
	v_add_u32_e32 v17, v0, v4
	v_add_u32_e32 v17, v17, v2
	v_add_u32_e32 v17, v17, v3
	v_add_u32_e32 v17, v17, v5
	v_add_u32_e32 v17, v17, v6
	v_add_u32_e32 v17, v17, v7
	v_add_u32_e32 v17, v17, v8
	v_add_u32_e32 v17, v17, v9
	v_add_u32_e32 v17, v17, v10
	v_add_u32_e32 v17, v17, v11
	v_add_u32_e32 v17, v17, v12
	v_add_u32_e32 v17, v17, v13
	v_add_u32_e32 v17, v17, v14
	v_add_u32_e32 v17, v17, v15
	v_add_u32_e32 v17, v17, v16
	v_cmp_eq_u32_e32 vcc, s81, v17
	s_cbranch_vccnz .LBB0_1080
	s_and_b32 s8, s14, 0xff
	s_cmp_eq_u32 s8, 0
	s_mov_b64 s[8:9], -1
	s_mov_b64 s[12:13], -1
	s_sleep 1
	s_cbranch_scc1 .LBB0_1085
	s_and_b64 vcc, exec, s[12:13]
	s_cbranch_vccz .LBB0_1080
